# attention: head-window setup loads and first queue atomic issued together up front; per-unit Q loads issued with the window-search loads
# speedup vs baseline: 1.0161x; 1.0078x over previous
; template<int THRL> __device__ __forceinline__ void fox_attn_phase(char*lds,const bf16*Q,const bf16*K,const bf16*V,bf16*O,const bf16*G,const float*__restrict__ cumf,unsigned*counter,float TH,float mfix){
;     ...
;   { const int nbr=4*(NQB-1);
;     for(int hh=0;hh<4;++hh){ const int bhh=wid*4+hh; const float* cfr=cumf+(long)bhh*SEQ; const float crefr=cfr[(NQB-1)*QB];
;       bool k0=true,k1=true; if(lane<nbr) k0=(crefr-cfr[64*lane+63])>=-TH; if(lane+64<nbr) k1=(crefr-cfr[64*(lane+64)+63])>=-TH;
;       const unsigned long long m0=__ballot(k0), m1=__ballot(k1);
;       int first=m0?__builtin_ctzll(m0):(m1?64+__builtin_ctzll(m1):128); if(first>nbr)first=nbr;
;       if(lane==0) Wb[bhh]=nbr-first; }
; __global__ void __launch_bounds__(NTHR, 2) fwd_megakernel(Args args) {
;     ...
;         float mq = 0.f, mk = 0.f;
;         { int tid = threadIdx.x; asm volatile("" : "+v"(tid)); const int lane = tid & 63; mq = fabsf(args.in[13][lane]); mk = fabsf(args.in[14][lane]);
; #pragma unroll
;           for (int o = 1; o < 64; o <<= 1) { mq = fmaxf(mq, __shfl_xor(mq, o)); mk = fmaxf(mk, __shfl_xor(mk, o)); } }
;         const float TH = 30.f + 2.f * 8.f * mq * mk * 1.01f;
.LBB0_804:
	s_or_b64 exec, exec, s[0:1]
	s_waitcnt lgkmcnt(0)
	v_mov_b32_e32 v0, v216
	s_barrier
	v_readfirstlane_b32 s17, v216
	v_and_b32_e32 v0, 63, v0
	v_lshlrev_b32_e32 v0, 2, v0
	global_load_dword v1, v0, s[62:63]
	s_nop 0
	global_load_dword v0, v0, s[64:65]
	s_add_u32 s62, s10, 0x1700000
	s_addc_u32 s63, s11, 0
	s_lshr_b32 s16, s17, 6
	s_mov_b32 s5, 0
	s_lshl_b32 s4, s16, 2
	s_lshl_b64 s[14:15], s[4:5], 15
	v_and_b32_e32 v217, 63, v216
	s_add_u32 s18, s62, s14
	v_mov_b32_e32 v2, 0x7000
	v_lshlrev_b32_e32 v3, 8, v217
	s_addc_u32 s19, s63, s15
	global_load_dword v2, v2, s[18:19] offset:3072
	s_nop 0
	global_load_dword v3, v3, s[18:19] offset:252
	v_mov_b32_e32 v35, 0x7000
	v_lshlrev_b32_e32 v45, 8, v217
	v_add_u32_e32 v46, 0x4000, v45
	s_add_u32 s98, s18, 0x8000
	s_addc_u32 s99, s19, 0
	global_load_dword v36, v35, s[98:99] offset:3072
	global_load_dword v37, v45, s[98:99] offset:252
	global_load_dword v38, v46, s[98:99] offset:252
	s_add_u32 s98, s98, 0x8000
	s_addc_u32 s99, s99, 0
	global_load_dword v39, v35, s[98:99] offset:3072
	global_load_dword v40, v45, s[98:99] offset:252
	global_load_dword v41, v46, s[98:99] offset:252
	s_add_u32 s98, s98, 0x8000
	s_addc_u32 s99, s99, 0
	global_load_dword v42, v35, s[98:99] offset:3072
	global_load_dword v43, v45, s[98:99] offset:252
	global_load_dword v44, v46, s[98:99] offset:252
	s_and_saveexec_b64 s[100:101], s[92:93]
	v_mov_b32_e32 v47, 0
	v_mov_b32_e32 v48, 1
	global_atomic_add v47, v47, v48, s[10:11] offset:256 sc0
	s_mov_b64 exec, s[100:101]
	v_cmp_lt_i32_e32 vcc, v215, v209
	v_or_b32_e32 v219, 64, v217
	s_movk_i32 s5, 0x7c
	v_cndmask_b32_e32 v4, v208, v215, vcc
	v_lshlrev_b32_e32 v4, 2, v4
	v_cmp_lt_i32_e32 vcc, v214, v209
	v_mov_b32_e32 v218, 0x41f00000
	s_mov_b64 s[40:41], -1
	v_cndmask_b32_e32 v5, v208, v214, vcc
	v_lshlrev_b32_e32 v5, 2, v5
	v_cmp_lt_i32_e32 vcc, v213, v209
	v_cmp_gt_u32_e64 s[36:37], s5, v219
	s_mov_b64 s[38:39], -1
	v_cndmask_b32_e32 v6, v208, v213, vcc
	v_lshlrev_b32_e32 v6, 2, v6
	v_cmp_lt_i32_e32 vcc, v212, v209
	s_waitcnt vmcnt(3)
	v_and_b32_e32 v7, 0x7fffffff, v1
	s_waitcnt vmcnt(2)
	v_and_b32_e32 v8, 0x7fffffff, v0
	ds_bpermute_b32 v7, v4, v7
	ds_bpermute_b32 v4, v4, v8
	v_max_f32_e64 v1, |v1|, |v1|
	v_max_f32_e64 v0, |v0|, |v0|
	s_waitcnt lgkmcnt(1)
	v_max_f32_e32 v7, v7, v7
	s_waitcnt lgkmcnt(0)
	v_max_f32_e32 v4, v4, v4
	v_max_f32_e32 v1, v1, v7
	v_max_f32_e32 v0, v0, v4
	ds_bpermute_b32 v4, v5, v1
	ds_bpermute_b32 v5, v5, v0
	v_cndmask_b32_e32 v7, v208, v212, vcc
	v_lshlrev_b32_e32 v7, 2, v7
	v_cmp_lt_i32_e32 vcc, v211, v209
	s_waitcnt lgkmcnt(1)
	v_max_f32_e32 v4, v4, v4
	s_waitcnt lgkmcnt(0)
	v_max_f32_e32 v5, v5, v5
	v_max_f32_e32 v1, v1, v4
	v_max_f32_e32 v0, v0, v5
	ds_bpermute_b32 v4, v6, v1
	ds_bpermute_b32 v5, v6, v0
	v_cndmask_b32_e32 v6, v208, v211, vcc
	v_lshlrev_b32_e32 v6, 2, v6
	v_cmp_lt_i32_e32 vcc, v210, v209
	s_waitcnt lgkmcnt(1)
	v_max_f32_e32 v4, v4, v4
	s_waitcnt lgkmcnt(0)
	v_max_f32_e32 v5, v5, v5
	v_max_f32_e32 v1, v1, v4
	v_max_f32_e32 v0, v0, v5
	ds_bpermute_b32 v4, v7, v1
	ds_bpermute_b32 v5, v7, v0
	v_cndmask_b32_e32 v7, v208, v210, vcc
	s_waitcnt lgkmcnt(1)
	v_max_f32_e32 v4, v4, v4
	s_waitcnt lgkmcnt(0)
	v_max_f32_e32 v5, v5, v5
	v_max_f32_e32 v1, v1, v4
	v_max_f32_e32 v0, v0, v5
	ds_bpermute_b32 v4, v6, v1
	ds_bpermute_b32 v5, v6, v0
	v_lshlrev_b32_e32 v6, 2, v7
	s_waitcnt lgkmcnt(1)
	v_max_f32_e32 v4, v4, v4
	s_waitcnt lgkmcnt(0)
	v_max_f32_e32 v5, v5, v5
	v_max_f32_e32 v1, v1, v4
	v_max_f32_e32 v4, v0, v5
	ds_bpermute_b32 v0, v6, v1
	ds_bpermute_b32 v5, v6, v4
	v_lshlrev_b32_e32 v6, 6, v219
	v_lshlrev_b32_e32 v220, 2, v6
	s_waitcnt lgkmcnt(1)
	v_max_f32_e32 v0, v0, v0
	s_waitcnt lgkmcnt(0)
	v_max_f32_e32 v5, v5, v5
	v_max_f32_e32 v0, v1, v0
	v_max_f32_e32 v1, v4, v5
	v_mul_f32_e32 v4, 0x41800000, v0
	v_mul_f32_e32 v4, v1, v4
	v_fmac_f32_e32 v218, 0x3f8147ae, v4
	s_and_saveexec_b64 s[42:43], s[36:37]
	s_cbranch_execz .LBB0_806
	global_load_dword v4, v220, s[18:19] offset:252
	s_waitcnt vmcnt(0)
	v_sub_f32_e32 v4, v2, v4
	v_cmp_ge_f32_e64 s[14:15], v4, -v218
	s_orn2_b64 s[38:39], s[14:15], exec

; template<int THRL> __device__ __forceinline__ void fox_attn_phase(char*lds,const bf16*Q,const bf16*K,const bf16*V,bf16*O,const bf16*G,const float*__restrict__ cumf,unsigned*counter,float TH,float mfix){
;     ...
;     for(int hh=0;hh<4;++hh){ const int bhh=wid*4+hh; const float* cfr=cumf+(long)bhh*SEQ; const float crefr=cfr[(NQB-1)*QB];
;       bool k0=true,k1=true; if(lane<nbr) k0=(crefr-cfr[64*lane+63])>=-TH; if(lane+64<nbr) k1=(crefr-cfr[64*(lane+64)+63])>=-TH;
;       const unsigned long long m0=__ballot(k0), m1=__ballot(k1);
;       int first=m0?__builtin_ctzll(m0):(m1?64+__builtin_ctzll(m1):128); if(first>nbr)first=nbr;
;       if(lane==0) Wb[bhh]=nbr-first; }
.LBB0_811:
	s_or_b64 exec, exec, s[40:41]
	s_or_b32 s18, s4, 1
	s_lshl_b64 s[14:15], s[18:19], 15
	s_add_u32 s40, s62, s14
	s_addc_u32 s41, s63, s15
	v_mov_b32_e32 v3, 0x7000
	v_lshlrev_b32_e32 v221, 2, v2
	v_mov_b32_e32 v2, v36
	s_nop 0
	v_mov_b32_e32 v3, v37
	s_mov_b64 s[42:43], -1
	s_mov_b64 s[44:45], -1
	s_and_saveexec_b64 s[46:47], s[36:37]
	s_cbranch_execz .LBB0_813
	v_mov_b32_e32 v4, v38
	s_waitcnt vmcnt(0)
	v_sub_f32_e32 v4, v2, v4
	v_cmp_ge_f32_e64 s[14:15], v4, -v218
	s_orn2_b64 s[44:45], s[14:15], exec

; template<int THRL> __device__ __forceinline__ void fox_attn_phase(char*lds,const bf16*Q,const bf16*K,const bf16*V,bf16*O,const bf16*G,const float*__restrict__ cumf,unsigned*counter,float TH,float mfix){
;     ...
;     for(int hh=0;hh<4;++hh){ const int bhh=wid*4+hh; const float* cfr=cumf+(long)bhh*SEQ; const float crefr=cfr[(NQB-1)*QB];
;       bool k0=true,k1=true; if(lane<nbr) k0=(crefr-cfr[64*lane+63])>=-TH; if(lane+64<nbr) k1=(crefr-cfr[64*(lane+64)+63])>=-TH;
;       const unsigned long long m0=__ballot(k0), m1=__ballot(k1);
;       int first=m0?__builtin_ctzll(m0):(m1?64+__builtin_ctzll(m1):128); if(first>nbr)first=nbr;
;       if(lane==0) Wb[bhh]=nbr-first; }
.LBB0_818:
	s_or_b64 exec, exec, s[40:41]
	s_or_b32 s18, s4, 2
	s_lshl_b64 s[14:15], s[18:19], 15
	s_add_u32 s40, s62, s14
	s_addc_u32 s41, s63, s15
	v_mov_b32_e32 v2, 0x7000
	v_mov_b32_e32 v2, v39
	s_nop 0
	v_mov_b32_e32 v3, v40
	s_mov_b64 s[42:43], -1
	s_mov_b64 s[44:45], -1
	s_and_saveexec_b64 s[46:47], s[36:37]
	s_cbranch_execz .LBB0_820
	v_mov_b32_e32 v4, v41
	s_waitcnt vmcnt(0)
	v_sub_f32_e32 v4, v2, v4
	v_cmp_ge_f32_e64 s[14:15], v4, -v218
	s_orn2_b64 s[44:45], s[14:15], exec

; template<int THRL> __device__ __forceinline__ void fox_attn_phase(char*lds,const bf16*Q,const bf16*K,const bf16*V,bf16*O,const bf16*G,const float*__restrict__ cumf,unsigned*counter,float TH,float mfix){
;     ...
;     for(int hh=0;hh<4;++hh){ const int bhh=wid*4+hh; const float* cfr=cumf+(long)bhh*SEQ; const float crefr=cfr[(NQB-1)*QB];
;       bool k0=true,k1=true; if(lane<nbr) k0=(crefr-cfr[64*lane+63])>=-TH; if(lane+64<nbr) k1=(crefr-cfr[64*(lane+64)+63])>=-TH;
;       const unsigned long long m0=__ballot(k0), m1=__ballot(k1);
;       int first=m0?__builtin_ctzll(m0):(m1?64+__builtin_ctzll(m1):128); if(first>nbr)first=nbr;
;       if(lane==0) Wb[bhh]=nbr-first; }
.LBB0_825:
	s_or_b64 exec, exec, s[40:41]
	s_or_b32 s4, s4, 3
	s_mov_b32 s5, 0
	s_lshl_b64 s[14:15], s[4:5], 15
	s_add_u32 s40, s62, s14
	s_addc_u32 s41, s63, s15
	v_mov_b32_e32 v2, 0x7000
	v_mov_b32_e32 v2, v42
	s_nop 0
	v_mov_b32_e32 v3, v43
	s_mov_b64 s[18:19], -1
	s_mov_b64 s[42:43], -1
	s_and_saveexec_b64 s[44:45], s[36:37]
	s_cbranch_execz .LBB0_827
	v_mov_b32_e32 v4, v44
	s_waitcnt vmcnt(0)
	v_sub_f32_e32 v4, v2, v4
	v_cmp_ge_f32_e64 s[14:15], v4, -v218
	s_orn2_b64 s[42:43], s[14:15], exec

; template<int THRL> __device__ __forceinline__ void fox_attn_phase(char*lds,const bf16*Q,const bf16*K,const bf16*V,bf16*O,const bf16*G,const float*__restrict__ cumf,unsigned*counter,float TH,float mfix){
;     ...
;     if(tid==0) shi[0]=(int)atomicAdd(counter,1u);
.LBB0_833:
	s_mov_b64 s[36:37], exec
	v_mbcnt_lo_u32_b32 v2, s36, 0
	v_mbcnt_hi_u32_b32 v2, s37, v2
	v_cmp_eq_u32_e32 vcc, 0, v2
	s_and_saveexec_b64 s[18:19], vcc
	s_cbranch_execz .LBB0_835
	s_bcnt1_i32_b64 s14, s[36:37]
	v_mov_b32_e32 v3, 0
	v_mov_b32_e32 v4, s14
	v_mov_b32_e32 v3, v47

; template<int THRL> __device__ __forceinline__ void attn_unit(int b,int h,int qb,int t0,float cqv,float mfix,const float*__restrict__ cf,float cref,unsigned*counter,const bf16*Q,const bf16*__restrict__ K,const bf16*__restrict__ V,bf16*O,const bf16*__restrict__ G,char*shm){
;     ...
;   for(int d0=0;d0<4;++d0)qr[d0]=*reinterpret_cast<const bf16x8*>(&Qw[(long)r32*DM+d0*16+hi*8]);
; template<int THRL> __device__ __forceinline__ void fox_attn_phase(char*lds,const bf16*Q,const bf16*K,const bf16*V,bf16*O,const bf16*G,const float*__restrict__ cumf,unsigned*counter,float TH,float mfix){
;     ...
;     const int u=shi[0];
;     if(u>=NQB*BATCH*NHEAD) break;
;     const int qb=NQB-1-(u&31), bh=sorted[u>>5], q0=qb*QB;
;     const float* cf=cumf+(long)bh*SEQ;
;     const float cref=cf[q0];
;     const int nb=4*qb; float e0=0.f,e1=0.f;
;     if(lane<nb) e0=cf[64*lane+63];
;     if(lane+64<nb) e1=cf[64*(lane+64)+63];
;     const float cqr=cf[q0+wid*QBLK+(lane&31)];
.LBB0_845:
	s_andn2_b32 s17, 31, s4
	s_ashr_i32 s4, s4, 5
	s_lshl_b32 s4, s4, 2
	s_add_i32 s4, s4, 0
	s_add_i32 s4, s4, 0x1c8c0
	v_mov_b32_e32 v0, s4
	ds_read_b32 v0, v0
	s_lshl_b32 s40, s17, 10
	v_mov_b32_e32 v4, s40
	s_lshl_b32 s70, s17, 2
	v_cmp_le_u32_e32 vcc, s70, v217
	s_waitcnt lgkmcnt(0)
	v_ashrrev_i32_e32 v1, 31, v0
	v_readfirstlane_b32 s16, v0
	v_lshlrev_b64 v[0:1], 15, v[0:1]
	v_lshl_add_u64 v[2:3], s[62:63], 0, v[0:1]
	s_nop 0
	v_readfirstlane_b32 s4, v2
	v_readfirstlane_b32 s5, v3
	s_nop 4
	global_load_dword v36, v4, s[4:5]
	v_readfirstlane_b32 s100, v216
	v_and_b32_e32 v250, 31, v217
	v_lshrrev_b32_e32 v251, 5, v217
	v_lshlrev_b32_e32 v250, 11, v250
	v_lshl_or_b32 v250, v251, 4, v250
	s_lshr_b32 s100, s100, 6
	s_lshl_b32 s100, s100, 5
	s_lshr_b32 s101, s16, 4
	s_lshl_b32 s101, s101, 13
	s_add_i32 s100, s100, s101
	s_lshl_b32 s101, s17, 8
	s_add_i32 s100, s100, s101
	s_lshl_b32 s100, s100, 11
	s_and_b32 s101, s16, 15
	s_lshl_b32 s101, s101, 7
	s_add_u32 s100, s100, s101
	s_add_u32 s98, s20, s100
	s_addc_u32 s99, s21, 0
	global_load_dwordx4 v[124:127], v250, s[98:99]
	global_load_dwordx4 v[120:123], v250, s[98:99] offset:32
	global_load_dwordx4 v[116:119], v250, s[98:99] offset:64
	global_load_dwordx4 v[112:115], v250, s[98:99] offset:96
	v_cmp_gt_u32_e64 s[4:5], s70, v217
	v_mov_b32_e32 v4, 0
	s_and_saveexec_b64 s[18:19], s[4:5]
	s_cbranch_execz .LBB0_847
	v_readfirstlane_b32 s4, v2
	v_readfirstlane_b32 s5, v3
	s_nop 4
	global_load_dword v4, v221, s[4:5] offset:252

; #define WAIT_BAR(N) asm volatile("s_waitcnt vmcnt(" #N ") lgkmcnt(0)\n\ts_barrier":::"memory")
;   #define DMA_K(t,slot) glds16(ksrc+(long)(t)*KVBLK*DM,(unsigned)__builtin_amdgcn_readfirstlane(kdst+(slot)))
;   #define DMA_V(t,slot) glds16(vsrc+(long)(t)*KVBLK*DM,(unsigned)__builtin_amdgcn_readfirstlane(vdst+(slot)))
;   #define CMASK(P0,P1,t) do{int jb_=(t)-(NT-4); if(jb_>=0)cmask(P0,P1,jb_,qrel,hi);}while(0)
;   #define CMASK(P0,P1,t) do{}while(0)
;   #define CMASK(P0,P1,t) do{int jb_=(t)-(NT-4); if(jb_>=0)cmask(P0,P1,jb_,qrel,hi);}while(0)
; template<int THRL> __device__ __forceinline__ void attn_unit(int b,int h,int qb,int t0,float cqv,float mfix,const float*__restrict__ cf,float cref,unsigned*counter,const bf16*Q,const bf16*__restrict__ K,const bf16*__restrict__ V,bf16*O,const bf16*__restrict__ G,char*shm){
;     ...
;   const int NT=(q0+QB)/KVBLK-t0;
;   DMA_K(0,0);DMA_V(0,0);DMA_K(1,SLOTB);
;   { __attribute__((address_space(3))) float* CK=(__attribute__((address_space(3))) float*)((__attribute__((address_space(3))) char*)shm+LDS_CK);
;     for(int base=t0*64+tid;base<q0+QB;base+=4*NW*64){ float cv[4];
;       #pragma unroll
;       for(int j=0;j<4;++j){ const int idx=base+NW*64*j; cv[j]=(idx<q0+QB)?cf[idx]:0.f; }
;       #pragma unroll
;       for(int j=0;j<4;++j){ const int idx=base+NW*64*j; if(idx<q0+QB) CK[idx]=(cv[j]-cref)*1.4426950408889634f; } } }
;   bf16x8 qr[4];
;   #pragma unroll
;   for(int d0=0;d0<4;++d0)qr[d0]=*reinterpret_cast<const bf16x8*>(&Qw[(long)r32*DM+d0*16+hi*8]);
;   float mhat=mfix,l_reg=0.f;f32x16 o[2];o[0]=f32x16{};o[1]=f32x16{};const f32x16 negm=f32x16{};
;   const int qrel=wid*QBLK+r32;
;     ...
;   typedef float f32x4_t __attribute__((ext_vector_type(4)));
;     ...
;   bool resc=false;
;     ...
;   f32x16 pA0,pA1,pB0,pB1;
;   int sl_prev=0,sl_cur=0,sl_next=SLOTB;
;     ...
;   DMA_K(2,2*SLOTB);
;   WAIT_BAR(3);
;   qkt(pA0,pA1,Kbase,qr,negm,r32,hi);asm volatile("s_nop 15\n\ts_nop 7":"+v"(pA0),"+v"(pA1));BIAS(pA0,pA1,0);CMASK(pA0,pA1,0);
.LBB0_867:
	s_or_b64 exec, exec, s[54:55]
	s_lshl_b64 s[14:15], s[18:19], 13
	s_lshl_b32 s17, s65, 5
	s_or_b64 s[14:15], s[14:15], s[40:41]
	s_ashr_i32 s18, s17, 31
	s_add_u32 s36, s14, s17
	s_addc_u32 s37, s15, s18
	s_lshl_b64 s[14:15], s[36:37], 11
	s_add_u32 s14, s20, s14
	v_lshrrev_b32_e32 v227, 5, v224
	s_addc_u32 s15, s21, s15
	v_and_b32_e32 v204, 31, v226
	s_add_u32 s14, s14, s52
	v_lshlrev_b32_e32 v230, 4, v227
	s_addc_u32 s15, s15, s53
	v_lshl_or_b32 v0, v204, 11, v230
	s_lshr_b32 s14, s67, 6
	s_sub_i32 s58, s14, s4
	s_cmp_lg_u32 0, -1
	s_cselect_b32 s14, 0, 0
	s_add_i32 s14, s14, s16
	v_lshl_add_u64 v[0:1], v[32:33], 0, s[46:47]
	v_lshlrev_b32_e32 v2, 10, v227
	v_lshlrev_b32_e32 v3, 4, v204
	s_addk_i32 s14, 0x4000
	s_mov_b32 s15, m0
	s_mov_b32 m0, s14
	s_nop 0
	global_load_lds_dwordx4 v[0:1], off
	s_mov_b32 m0, s15
	v_add3_u32 v233, 0, v2, v3
	s_waitcnt vmcnt(3) lgkmcnt(0)
	s_barrier
	ds_read_b128 v[0:3], v233
	ds_read_b128 v[4:7], v233 offset:512
	ds_read_b128 v[38:41], v233 offset:2048
	ds_read_b128 v[42:45], v233 offset:2560
	s_waitcnt vmcnt(4)
	v_sub_f32_e32 v36, v37, v36
	s_mov_b32 s14, 0x3fb8aa3b
	v_fma_f32 v206, v36, s14, -v222
	s_lshl_b32 s14, s4, 8
	s_add_i32 s14, s14, 0
	v_add_u32_e32 v36, s14, v230
	v_add_u32_e32 v64, 0x14800, v36
	v_or_b32_e32 v231, s17, v204
	s_cmp_lt_i32 s58, 5
	v_lshlrev_b32_e32 v228, 2, v227
	s_waitcnt vmcnt(3) lgkmcnt(3)
	v_mfma_f32_32x32x16_bf16 v[16:31], v[0:3], v[124:127], 0
	s_waitcnt lgkmcnt(2)
	v_mfma_f32_32x32x16_bf16 v[0:15], v[4:7], v[124:127], 0
	s_waitcnt vmcnt(2) lgkmcnt(1)
	v_mfma_f32_32x32x16_bf16 v[16:31], v[38:41], v[120:123], v[16:31]
	s_waitcnt lgkmcnt(0)
	v_mfma_f32_32x32x16_bf16 v[0:15], v[42:45], v[120:123], v[0:15]
	ds_read_b128 v[38:41], v233 offset:4096
	ds_read_b128 v[42:45], v233 offset:4608
	s_waitcnt vmcnt(1) lgkmcnt(1)
	v_mfma_f32_32x32x16_bf16 v[16:31], v[38:41], v[116:119], v[16:31]
	ds_read_b128 v[38:41], v233 offset:6144
	s_waitcnt lgkmcnt(1)
	v_mfma_f32_32x32x16_bf16 v[0:15], v[42:45], v[116:119], v[0:15]
	ds_read_b128 v[42:45], v233 offset:6656
	s_waitcnt vmcnt(0) lgkmcnt(1)
	v_mfma_f32_32x32x16_bf16 v[16:31], v[38:41], v[112:115], v[16:31]
	s_waitcnt lgkmcnt(0)
	v_mfma_f32_32x32x16_bf16 v[0:15], v[42:45], v[112:115], v[0:15]
	s_nop 15
	s_nop 7
	ds_read_b128 v[36:39], v64
	ds_read_b128 v[40:43], v64 offset:32
	ds_read_b128 v[44:47], v64 offset:128
	ds_read_b128 v[48:51], v64 offset:160
	ds_read_b128 v[52:55], v64 offset:64
	ds_read_b128 v[56:59], v64 offset:96
	ds_read_b128 v[60:63], v64 offset:192
	ds_read_b128 v[64:67], v64 offset:224
	s_waitcnt lgkmcnt(7)
	v_sub_f32_e32 v37, v206, v37
	v_sub_f32_e32 v36, v206, v36
	v_sub_f32_e32 v39, v206, v39
	v_sub_f32_e32 v38, v206, v38
	s_waitcnt lgkmcnt(6)
	v_sub_f32_e32 v41, v206, v41
	v_sub_f32_e32 v40, v206, v40
	v_sub_f32_e32 v43, v206, v43
	v_sub_f32_e32 v42, v206, v42
	s_waitcnt lgkmcnt(3)
	v_sub_f32_e32 v53, v206, v53
	v_sub_f32_e32 v52, v206, v52
	v_sub_f32_e32 v55, v206, v55
	v_sub_f32_e32 v54, v206, v54
	s_waitcnt lgkmcnt(2)
	v_sub_f32_e32 v57, v206, v57
	v_sub_f32_e32 v56, v206, v56
	v_sub_f32_e32 v59, v206, v59
	v_sub_f32_e32 v58, v206, v58
	v_sub_f32_e32 v45, v206, v45
	v_sub_f32_e32 v44, v206, v44
	v_sub_f32_e32 v47, v206, v47
	v_sub_f32_e32 v46, v206, v46
	v_sub_f32_e32 v49, v206, v49
	v_sub_f32_e32 v48, v206, v48
	v_sub_f32_e32 v51, v206, v51
	v_sub_f32_e32 v50, v206, v50
	s_waitcnt lgkmcnt(1)
	v_sub_f32_e32 v61, v206, v61
	v_sub_f32_e32 v60, v206, v60
	v_sub_f32_e32 v63, v206, v63
	v_sub_f32_e32 v62, v206, v62
	s_waitcnt lgkmcnt(0)
	v_sub_f32_e32 v65, v206, v65
	v_sub_f32_e32 v64, v206, v64
	v_sub_f32_e32 v67, v206, v67
	v_sub_f32_e32 v66, v206, v66
	v_pk_add_f32 v[30:31], v[30:31], v[58:59]
	v_pk_add_f32 v[28:29], v[28:29], v[56:57]
	v_pk_add_f32 v[26:27], v[26:27], v[54:55]
	v_pk_add_f32 v[24:25], v[24:25], v[52:53]
	v_pk_add_f32 v[22:23], v[22:23], v[42:43]
	v_pk_add_f32 v[20:21], v[20:21], v[40:41]
	v_pk_add_f32 v[18:19], v[18:19], v[38:39]
	v_pk_add_f32 v[16:17], v[16:17], v[36:37]
	v_pk_add_f32 v[14:15], v[14:15], v[66:67]
	v_pk_add_f32 v[12:13], v[12:13], v[64:65]
	v_pk_add_f32 v[10:11], v[10:11], v[62:63]
	v_pk_add_f32 v[8:9], v[8:9], v[60:61]
	v_pk_add_f32 v[6:7], v[6:7], v[50:51]
	v_pk_add_f32 v[4:5], v[4:5], v[48:49]
	v_pk_add_f32 v[2:3], v[2:3], v[46:47]
	v_pk_add_f32 v[0:1], v[0:1], v[44:45]
	s_cbranch_scc0 .LBB0_869
; __device__ __forceinline__ void cmask(f32x16&p0,f32x16&p1,int jb,int qrel,int hi){
;   const float NEG=-INFINITY; int kb=64*jb+4*hi;
;   #pragma unroll
;   for(int r=0;r<16;++r){int kv=kb+(r&3)+8*(r>>2); if(kv>qrel)p0[r]=NEG; if(kv+32>qrel)p1[r]=NEG;}
; }
	s_lshl_b32 s14, s58, 6
	v_subrev_u32_e32 v36, s14, v228
	v_add_u32_e32 v38, 0x120, v36
	v_add_u32_e32 v37, 0x100, v36
	v_cmp_le_i32_e32 vcc, v38, v231
	s_nop 1
	v_cndmask_b32_e32 v0, v223, v0, vcc
	v_cmp_lt_i32_e32 vcc, v37, v231
	s_nop 1
	v_cndmask_b32_e32 v17, v223, v17, vcc
	v_cmp_le_i32_e32 vcc, v37, v231
	v_add_u32_e32 v37, 0x121, v36
	s_nop 0
	v_cndmask_b32_e32 v16, v223, v16, vcc
	v_cmp_le_i32_e32 vcc, v37, v231
	v_add_u32_e32 v37, 0x102, v36
	s_nop 0
	v_cndmask_b32_e32 v1, v223, v1, vcc
	v_cmp_le_i32_e32 vcc, v37, v231
	v_add_u32_e32 v37, 0x122, v36
	s_nop 0
	v_cndmask_b32_e32 v18, v223, v18, vcc
	v_cmp_le_i32_e32 vcc, v37, v231
	v_add_u32_e32 v37, 0x103, v36
	s_nop 0
	v_cndmask_b32_e32 v2, v223, v2, vcc
	v_cmp_le_i32_e32 vcc, v37, v231
	v_add_u32_e32 v37, 0x123, v36
	s_nop 0
	v_cndmask_b32_e32 v19, v223, v19, vcc
	v_cmp_le_i32_e32 vcc, v37, v231
	v_add_u32_e32 v37, 0x108, v36
	s_nop 0
	v_cndmask_b32_e32 v3, v223, v3, vcc
	v_cmp_le_i32_e32 vcc, v37, v231
	v_add_u32_e32 v37, 0x128, v36
	s_nop 0
	v_cndmask_b32_e32 v20, v223, v20, vcc
	v_cmp_le_i32_e32 vcc, v37, v231
	v_add_u32_e32 v37, 0x109, v36
	s_nop 0
	v_cndmask_b32_e32 v4, v223, v4, vcc
	v_cmp_le_i32_e32 vcc, v37, v231
	v_add_u32_e32 v37, 0x129, v36
	s_nop 0
	v_cndmask_b32_e32 v21, v223, v21, vcc
	v_cmp_le_i32_e32 vcc, v37, v231
	v_add_u32_e32 v37, 0x10a, v36
	s_nop 0
	v_cndmask_b32_e32 v5, v223, v5, vcc
	v_cmp_le_i32_e32 vcc, v37, v231
	v_add_u32_e32 v37, 0x12a, v36
	s_nop 0
	v_cndmask_b32_e32 v22, v223, v22, vcc
	v_cmp_le_i32_e32 vcc, v37, v231
	v_add_u32_e32 v37, 0x10b, v36
	s_nop 0
	v_cndmask_b32_e32 v6, v223, v6, vcc
	v_cmp_le_i32_e32 vcc, v37, v231
	v_add_u32_e32 v37, 0x12b, v36
	s_nop 0
	v_cndmask_b32_e32 v23, v223, v23, vcc
	v_cmp_le_i32_e32 vcc, v37, v231
	v_add_u32_e32 v37, 0x110, v36
	s_nop 0
	v_cndmask_b32_e32 v7, v223, v7, vcc
	v_cmp_le_i32_e32 vcc, v37, v231
	v_add_u32_e32 v37, 0x130, v36
	s_nop 0
	v_cndmask_b32_e32 v24, v223, v24, vcc
	v_cmp_le_i32_e32 vcc, v37, v231
	v_add_u32_e32 v37, 0x111, v36
	s_nop 0
	v_cndmask_b32_e32 v8, v223, v8, vcc
	v_cmp_le_i32_e32 vcc, v37, v231
	v_add_u32_e32 v37, 0x131, v36
	s_nop 0
	v_cndmask_b32_e32 v25, v223, v25, vcc
	v_cmp_le_i32_e32 vcc, v37, v231
	v_add_u32_e32 v37, 0x112, v36
	s_nop 0
	v_cndmask_b32_e32 v9, v223, v9, vcc
	v_cmp_le_i32_e32 vcc, v37, v231
	v_add_u32_e32 v37, 0x132, v36
	s_nop 0
	v_cndmask_b32_e32 v26, v223, v26, vcc
	v_cmp_le_i32_e32 vcc, v37, v231
	v_add_u32_e32 v37, 0x113, v36
	s_nop 0
	v_cndmask_b32_e32 v10, v223, v10, vcc
	v_cmp_le_i32_e32 vcc, v37, v231
	v_add_u32_e32 v37, 0x133, v36
	s_nop 0
	v_cndmask_b32_e32 v27, v223, v27, vcc
	v_cmp_le_i32_e32 vcc, v37, v231
	v_add_u32_e32 v37, 0x118, v36
	s_nop 0
	v_cndmask_b32_e32 v11, v223, v11, vcc
	v_cmp_le_i32_e32 vcc, v37, v231
	v_add_u32_e32 v37, 0x138, v36
	s_nop 0
	v_cndmask_b32_e32 v28, v223, v28, vcc
	v_cmp_le_i32_e32 vcc, v37, v231
	v_add_u32_e32 v37, 0x119, v36
	s_nop 0
	v_cndmask_b32_e32 v12, v223, v12, vcc
	v_cmp_le_i32_e32 vcc, v37, v231
	v_add_u32_e32 v37, 0x139, v36
	s_nop 0
	v_cndmask_b32_e32 v29, v223, v29, vcc
	v_cmp_le_i32_e32 vcc, v37, v231
	v_add_u32_e32 v37, 0x11a, v36
	s_nop 0
	v_cndmask_b32_e32 v13, v223, v13, vcc
	v_cmp_le_i32_e32 vcc, v37, v231
	v_add_u32_e32 v37, 0x13a, v36
	s_nop 0
	v_cndmask_b32_e32 v30, v223, v30, vcc
	v_cmp_le_i32_e32 vcc, v37, v231
	v_add_u32_e32 v37, 0x11b, v36
	v_add_u32_e32 v36, 0x13b, v36
	v_cndmask_b32_e32 v14, v223, v14, vcc
	v_cmp_le_i32_e32 vcc, v37, v231
	s_nop 1
	v_cndmask_b32_e32 v31, v223, v31, vcc
	v_cmp_le_i32_e32 vcc, v36, v231
	s_nop 1
	v_cndmask_b32_e32 v15, v223, v15, vcc
